# v4 + GEMM K-loops: post-MFMA barrier arrives 3 MFMAs early, trailing MFMAs at prio 2
# speedup vs baseline: 1.0158x; 1.0030x over previous
.LBB0_229:
	ds_read_b128 v[144:147], v149
	ds_read_b128 v[154:157], v149 offset:1024
	ds_read_b128 v[158:161], v149 offset:2048
	ds_read_b128 v[162:165], v149 offset:3072
	ds_read_b128 v[166:169], v150
	ds_read_b128 v[170:173], v150 offset:1024
	ds_read_b128 v[174:177], v150 offset:2048
	ds_read_b128 v[178:181], v150 offset:3072
	s_add_u32 s30, s28, 0xfff00080
	s_addc_u32 s31, s29, -1
	s_cmp_eq_u32 s67, 60
	s_cselect_b32 s37, s21, s31
	s_cselect_b32 s36, s59, s30
	s_cselect_b32 s31, s19, s62
	s_cselect_b32 s30, s60, s61
	v_lshl_add_u64 v[214:215], s[28:29], 0, v[136:137]
	s_add_i32 m0, s27, 0xc000
	ds_read_b128 v[182:185], v151
	ds_read_b128 v[186:189], v151 offset:1024
	ds_read_b128 v[190:193], v151 offset:2048
	ds_read_b128 v[194:197], v151 offset:3072
	ds_read_b128 v[198:201], v151 offset:4096
	ds_read_b128 v[202:205], v151 offset:5120
	ds_read_b128 v[206:209], v151 offset:6144
	ds_read_b128 v[210:213], v151 offset:7168
	global_load_lds_dwordx4 v[214:215], off
	v_lshl_add_u64 v[214:215], s[28:29], 0, v[138:139]
	s_add_i32 m0, s27, 0xe000
	s_nop 0
	global_load_lds_dwordx4 v[214:215], off
	s_waitcnt vmcnt(8)
	s_waitcnt lgkmcnt(0)
	s_barrier
	s_setprio 1
	s_waitcnt lgkmcnt(0)
	v_mfma_f32_16x16x32_bf16 v[124:127], v[144:147], v[182:185], v[124:127]
	v_mfma_f32_16x16x32_bf16 v[120:123], v[158:161], v[182:185], v[120:123]
	v_mfma_f32_16x16x32_bf16 v[112:115], v[144:147], v[190:193], v[112:115]
	v_mfma_f32_16x16x32_bf16 v[104:107], v[158:161], v[190:193], v[104:107]
	v_mfma_f32_16x16x32_bf16 v[96:99], v[144:147], v[198:201], v[96:99]
	v_mfma_f32_16x16x32_bf16 v[88:91], v[158:161], v[198:201], v[88:91]
	v_mfma_f32_16x16x32_bf16 v[80:83], v[144:147], v[206:209], v[80:83]
	v_mfma_f32_16x16x32_bf16 v[72:75], v[158:161], v[206:209], v[72:75]
	v_mfma_f32_16x16x32_bf16 v[124:127], v[154:157], v[186:189], v[124:127]
	v_mfma_f32_16x16x32_bf16 v[120:123], v[162:165], v[186:189], v[120:123]
	v_mfma_f32_16x16x32_bf16 v[112:115], v[154:157], v[194:197], v[112:115]
	v_mfma_f32_16x16x32_bf16 v[104:107], v[162:165], v[194:197], v[104:107]
	v_mfma_f32_16x16x32_bf16 v[96:99], v[154:157], v[202:205], v[96:99]
	v_mfma_f32_16x16x32_bf16 v[88:91], v[162:165], v[202:205], v[88:91]
	v_mfma_f32_16x16x32_bf16 v[80:83], v[154:157], v[210:213], v[80:83]
	v_mfma_f32_16x16x32_bf16 v[72:75], v[162:165], v[210:213], v[72:75]
	s_setprio 0
	s_setprio 1
	v_mfma_f32_16x16x32_bf16 v[116:119], v[166:169], v[182:185], v[116:119]
	v_mfma_f32_16x16x32_bf16 v[108:111], v[174:177], v[182:185], v[108:111]
	v_mfma_f32_16x16x32_bf16 v[100:103], v[166:169], v[190:193], v[100:103]
	v_mfma_f32_16x16x32_bf16 v[92:95], v[174:177], v[190:193], v[92:95]
	v_mfma_f32_16x16x32_bf16 v[84:87], v[166:169], v[198:201], v[84:87]
	v_mfma_f32_16x16x32_bf16 v[76:79], v[174:177], v[198:201], v[76:79]
	v_mfma_f32_16x16x32_bf16 v[68:71], v[166:169], v[206:209], v[68:71]
	v_mfma_f32_16x16x32_bf16 v[64:67], v[174:177], v[206:209], v[64:67]
	v_mfma_f32_16x16x32_bf16 v[116:119], v[170:173], v[186:189], v[116:119]
	v_mfma_f32_16x16x32_bf16 v[108:111], v[178:181], v[186:189], v[108:111]
	v_mfma_f32_16x16x32_bf16 v[100:103], v[170:173], v[194:197], v[100:103]
	v_mfma_f32_16x16x32_bf16 v[92:95], v[178:181], v[194:197], v[92:95]
	s_setprio 2
	s_barrier
	v_mfma_f32_16x16x32_bf16 v[84:87], v[170:173], v[202:205], v[84:87]
	v_mfma_f32_16x16x32_bf16 v[76:79], v[178:181], v[202:205], v[76:79]
	v_mfma_f32_16x16x32_bf16 v[68:71], v[170:173], v[210:213], v[68:71]
	v_mfma_f32_16x16x32_bf16 v[64:67], v[178:181], v[210:213], v[64:67]
	s_setprio 0
	s_add_i32 s68, s56, s46
	v_lshl_add_u64 v[214:215], s[30:31], 0, v[130:131]
	s_mov_b32 m0, s68
	ds_read_b128 v[182:185], v151 offset:16384
	ds_read_b128 v[186:189], v151 offset:17408
	ds_read_b128 v[190:193], v151 offset:18432
	ds_read_b128 v[194:197], v151 offset:19456
	ds_read_b128 v[198:201], v151 offset:20480
	ds_read_b128 v[202:205], v151 offset:21504
	ds_read_b128 v[206:209], v151 offset:22528
	ds_read_b128 v[210:213], v151 offset:23552
	global_load_lds_dwordx4 v[214:215], off
	s_add_i32 m0, s68, 0x2000
	s_add_u32 s68, s30, 0x100000
	v_lshl_add_u64 v[216:217], s[30:31], 0, v[134:135]
	s_addc_u32 s69, s31, 0
	s_add_i32 s70, s57, s46
	global_load_lds_dwordx4 v[216:217], off
	v_lshl_add_u64 v[218:219], s[68:69], 0, v[130:131]
	s_mov_b32 m0, s70
	v_lshl_add_u64 v[220:221], s[36:37], 0, v[132:133]
	global_load_lds_dwordx4 v[218:219], off
	v_lshl_add_u64 v[218:219], s[68:69], 0, v[134:135]
	s_add_i32 m0, s70, 0x2000
	s_nop 0
	global_load_lds_dwordx4 v[218:219], off
	v_lshl_add_u64 v[218:219], s[36:37], 0, v[128:129]
	s_mov_b32 m0, s27
	s_nop 0
	global_load_lds_dwordx4 v[218:219], off
	s_mov_b32 m0, s47
	s_nop 0
	global_load_lds_dwordx4 v[220:221], off
	s_waitcnt vmcnt(8)
	s_waitcnt lgkmcnt(0)
	s_barrier
	s_setprio 1
	s_waitcnt lgkmcnt(0)
	v_mfma_f32_16x16x32_bf16 v[60:63], v[144:147], v[182:185], v[60:63]
	v_mfma_f32_16x16x32_bf16 v[56:59], v[158:161], v[182:185], v[56:59]
	v_mfma_f32_16x16x32_bf16 v[48:51], v[144:147], v[190:193], v[48:51]
	v_mfma_f32_16x16x32_bf16 v[40:43], v[158:161], v[190:193], v[40:43]
	v_mfma_f32_16x16x32_bf16 v[32:35], v[144:147], v[198:201], v[32:35]
	v_mfma_f32_16x16x32_bf16 v[24:27], v[158:161], v[198:201], v[24:27]
	v_mfma_f32_16x16x32_bf16 v[16:19], v[144:147], v[206:209], v[16:19]
	v_mfma_f32_16x16x32_bf16 v[8:11], v[158:161], v[206:209], v[8:11]
	v_mfma_f32_16x16x32_bf16 v[60:63], v[154:157], v[186:189], v[60:63]
	v_mfma_f32_16x16x32_bf16 v[56:59], v[162:165], v[186:189], v[56:59]
	v_mfma_f32_16x16x32_bf16 v[48:51], v[154:157], v[194:197], v[48:51]
	v_mfma_f32_16x16x32_bf16 v[40:43], v[162:165], v[194:197], v[40:43]
	v_mfma_f32_16x16x32_bf16 v[32:35], v[154:157], v[202:205], v[32:35]
	v_mfma_f32_16x16x32_bf16 v[24:27], v[162:165], v[202:205], v[24:27]
	v_mfma_f32_16x16x32_bf16 v[16:19], v[154:157], v[210:213], v[16:19]
	v_mfma_f32_16x16x32_bf16 v[8:11], v[162:165], v[210:213], v[8:11]
	s_setprio 0
	s_setprio 1
	v_mfma_f32_16x16x32_bf16 v[52:55], v[166:169], v[182:185], v[52:55]
	v_mfma_f32_16x16x32_bf16 v[44:47], v[174:177], v[182:185], v[44:47]
	v_mfma_f32_16x16x32_bf16 v[36:39], v[166:169], v[190:193], v[36:39]
	v_mfma_f32_16x16x32_bf16 v[28:31], v[174:177], v[190:193], v[28:31]
	v_mfma_f32_16x16x32_bf16 v[20:23], v[166:169], v[198:201], v[20:23]
	v_mfma_f32_16x16x32_bf16 v[12:15], v[174:177], v[198:201], v[12:15]
	v_mfma_f32_16x16x32_bf16 v[4:7], v[166:169], v[206:209], v[4:7]
	v_mfma_f32_16x16x32_bf16 v[0:3], v[174:177], v[206:209], v[0:3]
	v_mfma_f32_16x16x32_bf16 v[52:55], v[170:173], v[186:189], v[52:55]
	v_mfma_f32_16x16x32_bf16 v[44:47], v[178:181], v[186:189], v[44:47]
	v_mfma_f32_16x16x32_bf16 v[36:39], v[170:173], v[194:197], v[36:39]
	v_mfma_f32_16x16x32_bf16 v[28:31], v[178:181], v[194:197], v[28:31]
	s_setprio 2
	s_barrier
	v_mfma_f32_16x16x32_bf16 v[20:23], v[170:173], v[202:205], v[20:23]
	v_mfma_f32_16x16x32_bf16 v[12:15], v[178:181], v[202:205], v[12:15]
	v_mfma_f32_16x16x32_bf16 v[4:7], v[170:173], v[210:213], v[4:7]
	v_mfma_f32_16x16x32_bf16 v[0:3], v[178:181], v[210:213], v[0:3]
	s_setprio 0
	s_add_i32 s68, 0, 0x18000
	v_add_u32_e32 v153, s68, v148
	s_add_i32 s69, 0, 0x1c000
	ds_read_b128 v[144:147], v153
	ds_read_b128 v[154:157], v153 offset:1024
	ds_read_b128 v[158:161], v153 offset:2048
	ds_read_b128 v[162:165], v153 offset:3072
	v_add_u32_e32 v153, s69, v148
	ds_read_b128 v[166:169], v153
	ds_read_b128 v[170:173], v153 offset:1024
	ds_read_b128 v[174:177], v153 offset:2048
	ds_read_b128 v[178:181], v153 offset:3072
	s_add_u32 s36, s36, 0x100000
	s_addc_u32 s37, s37, 0
	s_mov_b32 m0, s48
	v_lshl_add_u64 v[222:223], s[36:37], 0, v[128:129]
	ds_read_b128 v[182:185], v151 offset:32768
	ds_read_b128 v[186:189], v151 offset:33792
	ds_read_b128 v[190:193], v151 offset:34816
	ds_read_b128 v[194:197], v151 offset:35840
	ds_read_b128 v[198:201], v151 offset:36864
	ds_read_b128 v[202:205], v151 offset:37888
	ds_read_b128 v[206:209], v151 offset:38912
	ds_read_b128 v[210:213], v151 offset:39936
	global_load_lds_dwordx4 v[222:223], off
	v_lshl_add_u64 v[222:223], s[36:37], 0, v[132:133]
	s_mov_b32 m0, s49
	s_nop 0
	global_load_lds_dwordx4 v[222:223], off
	s_waitcnt vmcnt(8)
	s_waitcnt lgkmcnt(0)
	s_barrier
	s_setprio 1
	s_waitcnt lgkmcnt(0)
	v_mfma_f32_16x16x32_bf16 v[124:127], v[144:147], v[182:185], v[124:127]
	v_mfma_f32_16x16x32_bf16 v[120:123], v[158:161], v[182:185], v[120:123]
	v_mfma_f32_16x16x32_bf16 v[112:115], v[144:147], v[190:193], v[112:115]
	v_mfma_f32_16x16x32_bf16 v[104:107], v[158:161], v[190:193], v[104:107]
	v_mfma_f32_16x16x32_bf16 v[96:99], v[144:147], v[198:201], v[96:99]
	v_mfma_f32_16x16x32_bf16 v[88:91], v[158:161], v[198:201], v[88:91]
	v_mfma_f32_16x16x32_bf16 v[80:83], v[144:147], v[206:209], v[80:83]
	v_mfma_f32_16x16x32_bf16 v[72:75], v[158:161], v[206:209], v[72:75]
	v_mfma_f32_16x16x32_bf16 v[124:127], v[154:157], v[186:189], v[124:127]
	v_mfma_f32_16x16x32_bf16 v[120:123], v[162:165], v[186:189], v[120:123]
	v_mfma_f32_16x16x32_bf16 v[112:115], v[154:157], v[194:197], v[112:115]
	v_mfma_f32_16x16x32_bf16 v[104:107], v[162:165], v[194:197], v[104:107]
	v_mfma_f32_16x16x32_bf16 v[96:99], v[154:157], v[202:205], v[96:99]
	v_mfma_f32_16x16x32_bf16 v[88:91], v[162:165], v[202:205], v[88:91]
	v_mfma_f32_16x16x32_bf16 v[80:83], v[154:157], v[210:213], v[80:83]
	v_mfma_f32_16x16x32_bf16 v[72:75], v[162:165], v[210:213], v[72:75]
	s_setprio 0
	s_setprio 1
	v_mfma_f32_16x16x32_bf16 v[116:119], v[166:169], v[182:185], v[116:119]
	v_mfma_f32_16x16x32_bf16 v[108:111], v[174:177], v[182:185], v[108:111]
	v_mfma_f32_16x16x32_bf16 v[100:103], v[166:169], v[190:193], v[100:103]
	v_mfma_f32_16x16x32_bf16 v[92:95], v[174:177], v[190:193], v[92:95]
	v_mfma_f32_16x16x32_bf16 v[84:87], v[166:169], v[198:201], v[84:87]
	v_mfma_f32_16x16x32_bf16 v[76:79], v[174:177], v[198:201], v[76:79]
	v_mfma_f32_16x16x32_bf16 v[68:71], v[166:169], v[206:209], v[68:71]
	v_mfma_f32_16x16x32_bf16 v[64:67], v[174:177], v[206:209], v[64:67]
	v_mfma_f32_16x16x32_bf16 v[116:119], v[170:173], v[186:189], v[116:119]
	v_mfma_f32_16x16x32_bf16 v[108:111], v[178:181], v[186:189], v[108:111]
	v_mfma_f32_16x16x32_bf16 v[100:103], v[170:173], v[194:197], v[100:103]
	v_mfma_f32_16x16x32_bf16 v[92:95], v[178:181], v[194:197], v[92:95]
	s_setprio 2
	s_barrier
	v_mfma_f32_16x16x32_bf16 v[84:87], v[170:173], v[202:205], v[84:87]
	v_mfma_f32_16x16x32_bf16 v[76:79], v[178:181], v[202:205], v[76:79]
	v_mfma_f32_16x16x32_bf16 v[68:71], v[170:173], v[210:213], v[68:71]
	v_mfma_f32_16x16x32_bf16 v[64:67], v[178:181], v[210:213], v[64:67]
	s_setprio 0
	s_add_i32 s36, s68, s46
	v_lshl_add_u64 v[214:215], v[214:215], 0, s[14:15]
	s_mov_b32 m0, s36
	ds_read_b128 v[182:185], v151 offset:49152
	ds_read_b128 v[186:189], v151 offset:50176
	ds_read_b128 v[190:193], v151 offset:51200
	ds_read_b128 v[194:197], v151 offset:52224
	ds_read_b128 v[198:201], v151 offset:53248
	ds_read_b128 v[202:205], v151 offset:54272
	ds_read_b128 v[206:209], v151 offset:55296
	ds_read_b128 v[210:213], v151 offset:56320
	global_load_lds_dwordx4 v[214:215], off
	s_add_i32 m0, s36, 0x2000
	s_add_u32 s30, s30, 0x100080
	v_lshl_add_u64 v[214:215], v[216:217], 0, s[14:15]
	s_addc_u32 s31, s31, 0
	s_add_i32 s36, s69, s46
	global_load_lds_dwordx4 v[214:215], off
	v_lshl_add_u64 v[214:215], s[30:31], 0, v[130:131]
	s_mov_b32 m0, s36
	s_nop 0
	global_load_lds_dwordx4 v[214:215], off
	v_lshl_add_u64 v[214:215], s[30:31], 0, v[134:135]
	s_add_i32 m0, s36, 0x2000
	s_nop 0
	global_load_lds_dwordx4 v[214:215], off
	v_lshl_add_u64 v[214:215], v[218:219], 0, s[14:15]
	s_mov_b32 m0, s53
	s_nop 0
	global_load_lds_dwordx4 v[214:215], off
	v_lshl_add_u64 v[214:215], v[220:221], 0, s[14:15]
	s_mov_b32 m0, s54
	s_nop 0
	global_load_lds_dwordx4 v[214:215], off
	s_waitcnt vmcnt(8)
	s_waitcnt lgkmcnt(0)
	s_barrier
	s_setprio 1
	s_waitcnt lgkmcnt(0)
	v_mfma_f32_16x16x32_bf16 v[60:63], v[144:147], v[182:185], v[60:63]
	v_mfma_f32_16x16x32_bf16 v[56:59], v[158:161], v[182:185], v[56:59]
	v_mfma_f32_16x16x32_bf16 v[48:51], v[144:147], v[190:193], v[48:51]
	v_mfma_f32_16x16x32_bf16 v[40:43], v[158:161], v[190:193], v[40:43]
	v_mfma_f32_16x16x32_bf16 v[32:35], v[144:147], v[198:201], v[32:35]
	v_mfma_f32_16x16x32_bf16 v[24:27], v[158:161], v[198:201], v[24:27]
	v_mfma_f32_16x16x32_bf16 v[16:19], v[144:147], v[206:209], v[16:19]
	v_mfma_f32_16x16x32_bf16 v[8:11], v[158:161], v[206:209], v[8:11]
	v_mfma_f32_16x16x32_bf16 v[60:63], v[154:157], v[186:189], v[60:63]
	v_mfma_f32_16x16x32_bf16 v[56:59], v[162:165], v[186:189], v[56:59]
	v_mfma_f32_16x16x32_bf16 v[48:51], v[154:157], v[194:197], v[48:51]
	v_mfma_f32_16x16x32_bf16 v[40:43], v[162:165], v[194:197], v[40:43]
	v_mfma_f32_16x16x32_bf16 v[32:35], v[154:157], v[202:205], v[32:35]
	v_mfma_f32_16x16x32_bf16 v[24:27], v[162:165], v[202:205], v[24:27]
	v_mfma_f32_16x16x32_bf16 v[16:19], v[154:157], v[210:213], v[16:19]
	v_mfma_f32_16x16x32_bf16 v[8:11], v[162:165], v[210:213], v[8:11]
	s_setprio 0
	s_setprio 1
	v_mfma_f32_16x16x32_bf16 v[52:55], v[166:169], v[182:185], v[52:55]
	v_mfma_f32_16x16x32_bf16 v[44:47], v[174:177], v[182:185], v[44:47]
	v_mfma_f32_16x16x32_bf16 v[36:39], v[166:169], v[190:193], v[36:39]
	v_mfma_f32_16x16x32_bf16 v[28:31], v[174:177], v[190:193], v[28:31]
	v_mfma_f32_16x16x32_bf16 v[20:23], v[166:169], v[198:201], v[20:23]
	v_mfma_f32_16x16x32_bf16 v[12:15], v[174:177], v[198:201], v[12:15]
	v_mfma_f32_16x16x32_bf16 v[4:7], v[166:169], v[206:209], v[4:7]
	v_mfma_f32_16x16x32_bf16 v[0:3], v[174:177], v[206:209], v[0:3]
	v_mfma_f32_16x16x32_bf16 v[52:55], v[170:173], v[186:189], v[52:55]
	v_mfma_f32_16x16x32_bf16 v[44:47], v[178:181], v[186:189], v[44:47]
	v_mfma_f32_16x16x32_bf16 v[36:39], v[170:173], v[194:197], v[36:39]
	v_mfma_f32_16x16x32_bf16 v[28:31], v[178:181], v[194:197], v[28:31]
	s_setprio 2
	s_barrier
	v_mfma_f32_16x16x32_bf16 v[20:23], v[170:173], v[202:205], v[20:23]
	v_mfma_f32_16x16x32_bf16 v[12:15], v[178:181], v[202:205], v[12:15]
	v_mfma_f32_16x16x32_bf16 v[4:7], v[170:173], v[210:213], v[4:7]
	v_mfma_f32_16x16x32_bf16 v[0:3], v[178:181], v[210:213], v[0:3]
	s_setprio 0
	s_add_i32 s67, s67, 2
	s_add_u32 s28, s28, 0x100
	s_addc_u32 s29, s29, 0
	s_add_u32 s61, s61, 0x100
	s_addc_u32 s62, s62, 0
	s_cmp_gt_u32 s67, 61
	s_cbranch_scc0 .LBB0_229

.LBB0_633:
	v_add_u32_e32 v160, s68, v164
	v_add_u32_e32 v178, s69, v164
	s_add_u32 s48, s38, s46
	ds_read_b128 v[148:151], v160
	ds_read_b128 v[152:155], v160 offset:1024
	ds_read_b128 v[156:159], v160 offset:2048
	ds_read_b128 v[160:163], v160 offset:3072
	ds_read_b128 v[166:169], v178
	ds_read_b128 v[170:173], v178 offset:1024
	ds_read_b128 v[174:177], v178 offset:2048
	ds_read_b128 v[178:181], v178 offset:3072
	s_addc_u32 s49, s39, s47
	s_add_u32 s48, s48, 0x100
	s_addc_u32 s49, s49, 0
	s_add_u32 s67, s74, s46
	s_addc_u32 s77, s75, s47
	s_cmpk_eq_i32 s46, 0xf00
	s_cselect_b32 s51, s29, s49
	s_cselect_b32 s50, s71, s48
	s_cselect_b32 s49, s72, s77
	s_cselect_b32 s48, s73, s67
	v_lshl_add_u64 v[214:215], v[144:145], 0, s[46:47]
	s_add_i32 m0, s54, 0xc000
	ds_read_b128 v[182:185], v165
	ds_read_b128 v[186:189], v165 offset:1024
	ds_read_b128 v[190:193], v165 offset:2048
	ds_read_b128 v[194:197], v165 offset:3072
	ds_read_b128 v[198:201], v165 offset:4096
	ds_read_b128 v[202:205], v165 offset:5120
	ds_read_b128 v[206:209], v165 offset:6144
	ds_read_b128 v[210:213], v165 offset:7168
	global_load_lds_dwordx4 v[214:215], off
	v_lshl_add_u64 v[214:215], v[146:147], 0, s[46:47]
	s_add_i32 m0, s54, 0xe000
	s_nop 0
	global_load_lds_dwordx4 v[214:215], off
	s_waitcnt vmcnt(8)
	s_waitcnt lgkmcnt(0)
	s_barrier
	s_setprio 1
	s_waitcnt lgkmcnt(0)
	v_mfma_i32_16x16x64_i8 v[124:127], v[148:151], v[182:185], v[124:127]
	v_mfma_i32_16x16x64_i8 v[120:123], v[156:159], v[182:185], v[120:123]
	v_mfma_i32_16x16x64_i8 v[108:111], v[148:151], v[190:193], v[108:111]
	v_mfma_i32_16x16x64_i8 v[104:107], v[156:159], v[190:193], v[104:107]
	v_mfma_i32_16x16x64_i8 v[92:95], v[148:151], v[198:201], v[92:95]
	v_mfma_i32_16x16x64_i8 v[88:91], v[156:159], v[198:201], v[88:91]
	v_mfma_i32_16x16x64_i8 v[76:79], v[148:151], v[206:209], v[76:79]
	v_mfma_i32_16x16x64_i8 v[72:75], v[156:159], v[206:209], v[72:75]
	v_mfma_i32_16x16x64_i8 v[124:127], v[152:155], v[186:189], v[124:127]
	v_mfma_i32_16x16x64_i8 v[120:123], v[160:163], v[186:189], v[120:123]
	v_mfma_i32_16x16x64_i8 v[108:111], v[152:155], v[194:197], v[108:111]
	v_mfma_i32_16x16x64_i8 v[104:107], v[160:163], v[194:197], v[104:107]
	v_mfma_i32_16x16x64_i8 v[92:95], v[152:155], v[202:205], v[92:95]
	v_mfma_i32_16x16x64_i8 v[88:91], v[160:163], v[202:205], v[88:91]
	v_mfma_i32_16x16x64_i8 v[76:79], v[152:155], v[210:213], v[76:79]
	v_mfma_i32_16x16x64_i8 v[72:75], v[160:163], v[210:213], v[72:75]
	s_setprio 0
	s_setprio 1
	v_mfma_i32_16x16x64_i8 v[116:119], v[166:169], v[182:185], v[116:119]
	v_mfma_i32_16x16x64_i8 v[112:115], v[174:177], v[182:185], v[112:115]
	v_mfma_i32_16x16x64_i8 v[100:103], v[166:169], v[190:193], v[100:103]
	v_mfma_i32_16x16x64_i8 v[96:99], v[174:177], v[190:193], v[96:99]
	v_mfma_i32_16x16x64_i8 v[84:87], v[166:169], v[198:201], v[84:87]
	v_mfma_i32_16x16x64_i8 v[80:83], v[174:177], v[198:201], v[80:83]
	v_mfma_i32_16x16x64_i8 v[68:71], v[166:169], v[206:209], v[68:71]
	v_mfma_i32_16x16x64_i8 v[64:67], v[174:177], v[206:209], v[64:67]
	v_mfma_i32_16x16x64_i8 v[116:119], v[170:173], v[186:189], v[116:119]
	v_mfma_i32_16x16x64_i8 v[112:115], v[178:181], v[186:189], v[112:115]
	v_mfma_i32_16x16x64_i8 v[100:103], v[170:173], v[194:197], v[100:103]
	v_mfma_i32_16x16x64_i8 v[96:99], v[178:181], v[194:197], v[96:99]
	s_setprio 2
	s_barrier
	v_mfma_i32_16x16x64_i8 v[84:87], v[170:173], v[202:205], v[84:87]
	v_mfma_i32_16x16x64_i8 v[80:83], v[178:181], v[202:205], v[80:83]
	v_mfma_i32_16x16x64_i8 v[68:71], v[170:173], v[210:213], v[68:71]
	v_mfma_i32_16x16x64_i8 v[64:67], v[178:181], v[210:213], v[64:67]
	s_setprio 0
	s_add_i32 s67, s68, s45
	v_lshl_add_u64 v[214:215], s[48:49], 0, v[132:133]
	s_mov_b32 m0, s67
	ds_read_b128 v[182:185], v165 offset:16384
	ds_read_b128 v[186:189], v165 offset:17408
	ds_read_b128 v[190:193], v165 offset:18432
	ds_read_b128 v[194:197], v165 offset:19456
	ds_read_b128 v[198:201], v165 offset:20480
	ds_read_b128 v[202:205], v165 offset:21504
	ds_read_b128 v[206:209], v165 offset:22528
	ds_read_b128 v[210:213], v165 offset:23552
	global_load_lds_dwordx4 v[214:215], off
	s_add_i32 m0, s67, 0x2000
	s_add_u32 s78, s48, 0x80000
	v_lshl_add_u64 v[216:217], s[48:49], 0, v[128:129]
	s_addc_u32 s79, s49, 0
	s_add_i32 s67, s69, s45
	global_load_lds_dwordx4 v[216:217], off
	v_lshl_add_u64 v[218:219], s[78:79], 0, v[132:133]
	s_mov_b32 m0, s67
	v_lshl_add_u64 v[220:221], s[50:51], 0, v[130:131]
	global_load_lds_dwordx4 v[218:219], off
	v_lshl_add_u64 v[218:219], s[78:79], 0, v[128:129]
	s_add_i32 m0, s67, 0x2000
	s_nop 0
	global_load_lds_dwordx4 v[218:219], off
	v_lshl_add_u64 v[218:219], s[50:51], 0, v[134:135]
	s_mov_b32 m0, s54
	s_nop 0
	global_load_lds_dwordx4 v[218:219], off
	s_mov_b32 m0, s55
	s_nop 0
	global_load_lds_dwordx4 v[220:221], off
	s_waitcnt vmcnt(8)
	s_waitcnt lgkmcnt(0)
	s_barrier
	s_setprio 1
	s_waitcnt lgkmcnt(0)
	v_mfma_i32_16x16x64_i8 v[60:63], v[148:151], v[182:185], v[60:63]
	v_mfma_i32_16x16x64_i8 v[56:59], v[156:159], v[182:185], v[56:59]
	v_mfma_i32_16x16x64_i8 v[44:47], v[148:151], v[190:193], v[44:47]
	v_mfma_i32_16x16x64_i8 v[40:43], v[156:159], v[190:193], v[40:43]
	v_mfma_i32_16x16x64_i8 v[28:31], v[148:151], v[198:201], v[28:31]
	v_mfma_i32_16x16x64_i8 v[24:27], v[156:159], v[198:201], v[24:27]
	v_mfma_i32_16x16x64_i8 v[12:15], v[148:151], v[206:209], v[12:15]
	v_mfma_i32_16x16x64_i8 v[8:11], v[156:159], v[206:209], v[8:11]
	v_mfma_i32_16x16x64_i8 v[60:63], v[152:155], v[186:189], v[60:63]
	v_mfma_i32_16x16x64_i8 v[56:59], v[160:163], v[186:189], v[56:59]
	v_mfma_i32_16x16x64_i8 v[44:47], v[152:155], v[194:197], v[44:47]
	v_mfma_i32_16x16x64_i8 v[40:43], v[160:163], v[194:197], v[40:43]
	v_mfma_i32_16x16x64_i8 v[28:31], v[152:155], v[202:205], v[28:31]
	v_mfma_i32_16x16x64_i8 v[24:27], v[160:163], v[202:205], v[24:27]
	v_mfma_i32_16x16x64_i8 v[12:15], v[152:155], v[210:213], v[12:15]
	v_mfma_i32_16x16x64_i8 v[8:11], v[160:163], v[210:213], v[8:11]
	s_setprio 0
	s_setprio 1
	v_mfma_i32_16x16x64_i8 v[52:55], v[166:169], v[182:185], v[52:55]
	v_mfma_i32_16x16x64_i8 v[48:51], v[174:177], v[182:185], v[48:51]
	v_mfma_i32_16x16x64_i8 v[36:39], v[166:169], v[190:193], v[36:39]
	v_mfma_i32_16x16x64_i8 v[32:35], v[174:177], v[190:193], v[32:35]
	v_mfma_i32_16x16x64_i8 v[20:23], v[166:169], v[198:201], v[20:23]
	v_mfma_i32_16x16x64_i8 v[16:19], v[174:177], v[198:201], v[16:19]
	v_mfma_i32_16x16x64_i8 v[4:7], v[166:169], v[206:209], v[4:7]
	v_mfma_i32_16x16x64_i8 v[0:3], v[174:177], v[206:209], v[0:3]
	v_mfma_i32_16x16x64_i8 v[52:55], v[170:173], v[186:189], v[52:55]
	v_mfma_i32_16x16x64_i8 v[48:51], v[178:181], v[186:189], v[48:51]
	v_mfma_i32_16x16x64_i8 v[36:39], v[170:173], v[194:197], v[36:39]
	v_mfma_i32_16x16x64_i8 v[32:35], v[178:181], v[194:197], v[32:35]
	s_setprio 2
	s_barrier
	v_mfma_i32_16x16x64_i8 v[20:23], v[170:173], v[202:205], v[20:23]
	v_mfma_i32_16x16x64_i8 v[16:19], v[178:181], v[202:205], v[16:19]
	v_mfma_i32_16x16x64_i8 v[4:7], v[170:173], v[210:213], v[4:7]
	v_mfma_i32_16x16x64_i8 v[0:3], v[178:181], v[210:213], v[0:3]
	s_setprio 0
	s_add_i32 s67, 0, 0x18000
	s_add_i32 s77, 0, 0x1c000
	v_add_u32_e32 v160, s67, v164
	v_add_u32_e32 v178, s77, v164
	ds_read_b128 v[148:151], v160
	ds_read_b128 v[152:155], v160 offset:1024
	ds_read_b128 v[156:159], v160 offset:2048
	ds_read_b128 v[160:163], v160 offset:3072
	ds_read_b128 v[166:169], v178
	ds_read_b128 v[170:173], v178 offset:1024
	ds_read_b128 v[174:177], v178 offset:2048
	ds_read_b128 v[178:181], v178 offset:3072
	s_add_u32 s50, s50, 0x80000
	s_addc_u32 s51, s51, 0
	s_mov_b32 m0, s56
	v_lshl_add_u64 v[222:223], s[50:51], 0, v[134:135]
	ds_read_b128 v[182:185], v165 offset:32768
	ds_read_b128 v[186:189], v165 offset:33792
	ds_read_b128 v[190:193], v165 offset:34816
	ds_read_b128 v[194:197], v165 offset:35840
	ds_read_b128 v[198:201], v165 offset:36864
	ds_read_b128 v[202:205], v165 offset:37888
	ds_read_b128 v[206:209], v165 offset:38912
	ds_read_b128 v[210:213], v165 offset:39936
	global_load_lds_dwordx4 v[222:223], off
	v_lshl_add_u64 v[222:223], s[50:51], 0, v[130:131]
	s_mov_b32 m0, s57
	s_nop 0
	global_load_lds_dwordx4 v[222:223], off
	s_waitcnt vmcnt(8)
	s_waitcnt lgkmcnt(0)
	s_barrier
	s_setprio 1
	s_waitcnt lgkmcnt(0)
	v_mfma_i32_16x16x64_i8 v[124:127], v[148:151], v[182:185], v[124:127]
	v_mfma_i32_16x16x64_i8 v[120:123], v[156:159], v[182:185], v[120:123]
	v_mfma_i32_16x16x64_i8 v[108:111], v[148:151], v[190:193], v[108:111]
	v_mfma_i32_16x16x64_i8 v[104:107], v[156:159], v[190:193], v[104:107]
	v_mfma_i32_16x16x64_i8 v[92:95], v[148:151], v[198:201], v[92:95]
	v_mfma_i32_16x16x64_i8 v[88:91], v[156:159], v[198:201], v[88:91]
	v_mfma_i32_16x16x64_i8 v[76:79], v[148:151], v[206:209], v[76:79]
	v_mfma_i32_16x16x64_i8 v[72:75], v[156:159], v[206:209], v[72:75]
	v_mfma_i32_16x16x64_i8 v[124:127], v[152:155], v[186:189], v[124:127]
	v_mfma_i32_16x16x64_i8 v[120:123], v[160:163], v[186:189], v[120:123]
	v_mfma_i32_16x16x64_i8 v[108:111], v[152:155], v[194:197], v[108:111]
	v_mfma_i32_16x16x64_i8 v[104:107], v[160:163], v[194:197], v[104:107]
	v_mfma_i32_16x16x64_i8 v[92:95], v[152:155], v[202:205], v[92:95]
	v_mfma_i32_16x16x64_i8 v[88:91], v[160:163], v[202:205], v[88:91]
	v_mfma_i32_16x16x64_i8 v[76:79], v[152:155], v[210:213], v[76:79]
	v_mfma_i32_16x16x64_i8 v[72:75], v[160:163], v[210:213], v[72:75]
	s_setprio 0
	s_setprio 1
	v_mfma_i32_16x16x64_i8 v[116:119], v[166:169], v[182:185], v[116:119]
	v_mfma_i32_16x16x64_i8 v[112:115], v[174:177], v[182:185], v[112:115]
	v_mfma_i32_16x16x64_i8 v[100:103], v[166:169], v[190:193], v[100:103]
	v_mfma_i32_16x16x64_i8 v[96:99], v[174:177], v[190:193], v[96:99]
	v_mfma_i32_16x16x64_i8 v[84:87], v[166:169], v[198:201], v[84:87]
	v_mfma_i32_16x16x64_i8 v[80:83], v[174:177], v[198:201], v[80:83]
	v_mfma_i32_16x16x64_i8 v[68:71], v[166:169], v[206:209], v[68:71]
	v_mfma_i32_16x16x64_i8 v[64:67], v[174:177], v[206:209], v[64:67]
	v_mfma_i32_16x16x64_i8 v[116:119], v[170:173], v[186:189], v[116:119]
	v_mfma_i32_16x16x64_i8 v[112:115], v[178:181], v[186:189], v[112:115]
	v_mfma_i32_16x16x64_i8 v[100:103], v[170:173], v[194:197], v[100:103]
	v_mfma_i32_16x16x64_i8 v[96:99], v[178:181], v[194:197], v[96:99]
	s_setprio 2
	s_barrier
	v_mfma_i32_16x16x64_i8 v[84:87], v[170:173], v[202:205], v[84:87]
	v_mfma_i32_16x16x64_i8 v[80:83], v[178:181], v[202:205], v[80:83]
	v_mfma_i32_16x16x64_i8 v[68:71], v[170:173], v[210:213], v[68:71]
	v_mfma_i32_16x16x64_i8 v[64:67], v[178:181], v[210:213], v[64:67]
	s_setprio 0
	s_add_i32 s50, s67, s45
	v_lshl_add_u64 v[214:215], v[214:215], 0, s[18:19]
	s_mov_b32 m0, s50
	ds_read_b128 v[182:185], v165 offset:49152
	ds_read_b128 v[186:189], v165 offset:50176
	ds_read_b128 v[190:193], v165 offset:51200
	ds_read_b128 v[194:197], v165 offset:52224
	ds_read_b128 v[198:201], v165 offset:53248
	ds_read_b128 v[202:205], v165 offset:54272
	ds_read_b128 v[206:209], v165 offset:55296
	ds_read_b128 v[210:213], v165 offset:56320
	global_load_lds_dwordx4 v[214:215], off
	s_add_i32 m0, s50, 0x2000
	s_add_u32 s48, s48, 0x80080
	v_lshl_add_u64 v[214:215], v[216:217], 0, s[18:19]
	s_addc_u32 s49, s49, 0
	s_add_i32 s50, s77, s45
	global_load_lds_dwordx4 v[214:215], off
	v_lshl_add_u64 v[214:215], s[48:49], 0, v[132:133]
	s_mov_b32 m0, s50
	s_nop 0
	global_load_lds_dwordx4 v[214:215], off
	v_lshl_add_u64 v[214:215], s[48:49], 0, v[128:129]
	s_add_i32 m0, s50, 0x2000
	s_nop 0
	global_load_lds_dwordx4 v[214:215], off
	v_lshl_add_u64 v[214:215], v[218:219], 0, s[18:19]
	s_mov_b32 m0, s60
	s_nop 0
	global_load_lds_dwordx4 v[214:215], off
	v_lshl_add_u64 v[214:215], v[220:221], 0, s[18:19]
	s_mov_b32 m0, s61
	s_nop 0
	global_load_lds_dwordx4 v[214:215], off
	s_waitcnt vmcnt(8)
	s_waitcnt lgkmcnt(0)
	s_barrier
	s_setprio 1
	s_waitcnt lgkmcnt(0)
	v_mfma_i32_16x16x64_i8 v[60:63], v[148:151], v[182:185], v[60:63]
	v_mfma_i32_16x16x64_i8 v[56:59], v[156:159], v[182:185], v[56:59]
	v_mfma_i32_16x16x64_i8 v[44:47], v[148:151], v[190:193], v[44:47]
	v_mfma_i32_16x16x64_i8 v[40:43], v[156:159], v[190:193], v[40:43]
	v_mfma_i32_16x16x64_i8 v[28:31], v[148:151], v[198:201], v[28:31]
	v_mfma_i32_16x16x64_i8 v[24:27], v[156:159], v[198:201], v[24:27]
	v_mfma_i32_16x16x64_i8 v[12:15], v[148:151], v[206:209], v[12:15]
	v_mfma_i32_16x16x64_i8 v[8:11], v[156:159], v[206:209], v[8:11]
	v_mfma_i32_16x16x64_i8 v[60:63], v[152:155], v[186:189], v[60:63]
	v_mfma_i32_16x16x64_i8 v[56:59], v[160:163], v[186:189], v[56:59]
	v_mfma_i32_16x16x64_i8 v[44:47], v[152:155], v[194:197], v[44:47]
	v_mfma_i32_16x16x64_i8 v[40:43], v[160:163], v[194:197], v[40:43]
	v_mfma_i32_16x16x64_i8 v[28:31], v[152:155], v[202:205], v[28:31]
	v_mfma_i32_16x16x64_i8 v[24:27], v[160:163], v[202:205], v[24:27]
	v_mfma_i32_16x16x64_i8 v[12:15], v[152:155], v[210:213], v[12:15]
	v_mfma_i32_16x16x64_i8 v[8:11], v[160:163], v[210:213], v[8:11]
	s_setprio 0
	s_setprio 1
	v_mfma_i32_16x16x64_i8 v[52:55], v[166:169], v[182:185], v[52:55]
	v_mfma_i32_16x16x64_i8 v[48:51], v[174:177], v[182:185], v[48:51]
	v_mfma_i32_16x16x64_i8 v[36:39], v[166:169], v[190:193], v[36:39]
	v_mfma_i32_16x16x64_i8 v[32:35], v[174:177], v[190:193], v[32:35]
	v_mfma_i32_16x16x64_i8 v[20:23], v[166:169], v[198:201], v[20:23]
	v_mfma_i32_16x16x64_i8 v[16:19], v[174:177], v[198:201], v[16:19]
	v_mfma_i32_16x16x64_i8 v[4:7], v[166:169], v[206:209], v[4:7]
	v_mfma_i32_16x16x64_i8 v[0:3], v[174:177], v[206:209], v[0:3]
	v_mfma_i32_16x16x64_i8 v[52:55], v[170:173], v[186:189], v[52:55]
	v_mfma_i32_16x16x64_i8 v[48:51], v[178:181], v[186:189], v[48:51]
	v_mfma_i32_16x16x64_i8 v[36:39], v[170:173], v[194:197], v[36:39]
	v_mfma_i32_16x16x64_i8 v[32:35], v[178:181], v[194:197], v[32:35]
	s_setprio 2
	s_barrier
	v_mfma_i32_16x16x64_i8 v[20:23], v[170:173], v[202:205], v[20:23]
	v_mfma_i32_16x16x64_i8 v[16:19], v[178:181], v[202:205], v[16:19]
	v_mfma_i32_16x16x64_i8 v[4:7], v[170:173], v[210:213], v[4:7]
	v_mfma_i32_16x16x64_i8 v[0:3], v[178:181], v[210:213], v[0:3]
	s_setprio 0
	s_add_i32 s76, s76, 2
	s_add_u32 s46, s46, 0x100
	s_addc_u32 s47, s47, 0
	s_cmp_gt_u32 s76, 29
	s_cbranch_scc1 .LBB0_636

.LBB0_771:
	ds_read_b128 v[144:147], v153
	ds_read_b128 v[148:151], v153 offset:1024
	ds_read_b128 v[156:159], v153 offset:2048
	ds_read_b128 v[160:163], v153 offset:3072
	ds_read_b128 v[164:167], v154
	ds_read_b128 v[168:171], v154 offset:1024
	ds_read_b128 v[172:175], v154 offset:2048
	ds_read_b128 v[176:179], v154 offset:3072
	s_add_u32 s56, s54, 0xfff80080
	s_addc_u32 s57, s55, -1
	s_cmp_eq_u32 s79, 28
	s_cselect_b32 s59, s47, s57
	s_cselect_b32 s58, s75, s56
	s_cselect_b32 s57, s39, s78
	s_cselect_b32 s56, s76, s77
	v_lshl_add_u64 v[212:213], s[54:55], 0, v[136:137]
	s_add_i32 m0, s37, 0xc000
	ds_read_b128 v[180:183], v155
	ds_read_b128 v[184:187], v155 offset:1024
	ds_read_b128 v[188:191], v155 offset:2048
	ds_read_b128 v[192:195], v155 offset:3072
	ds_read_b128 v[196:199], v155 offset:4096
	ds_read_b128 v[200:203], v155 offset:5120
	ds_read_b128 v[204:207], v155 offset:6144
	ds_read_b128 v[208:211], v155 offset:7168
	global_load_lds_dwordx4 v[212:213], off
	v_lshl_add_u64 v[212:213], s[54:55], 0, v[138:139]
	s_add_i32 m0, s37, 0xe000
	s_nop 0
	global_load_lds_dwordx4 v[212:213], off
	s_waitcnt vmcnt(8)
	s_waitcnt lgkmcnt(0)
	s_barrier
	s_setprio 1
	s_waitcnt lgkmcnt(0)
	v_mfma_i32_16x16x64_i8 v[124:127], v[144:147], v[180:183], v[124:127]
	v_mfma_i32_16x16x64_i8 v[120:123], v[156:159], v[180:183], v[120:123]
	v_mfma_i32_16x16x64_i8 v[108:111], v[144:147], v[188:191], v[108:111]
	v_mfma_i32_16x16x64_i8 v[104:107], v[156:159], v[188:191], v[104:107]
	v_mfma_i32_16x16x64_i8 v[92:95], v[144:147], v[196:199], v[92:95]
	v_mfma_i32_16x16x64_i8 v[88:91], v[156:159], v[196:199], v[88:91]
	v_mfma_i32_16x16x64_i8 v[76:79], v[144:147], v[204:207], v[76:79]
	v_mfma_i32_16x16x64_i8 v[72:75], v[156:159], v[204:207], v[72:75]
	v_mfma_i32_16x16x64_i8 v[124:127], v[148:151], v[184:187], v[124:127]
	v_mfma_i32_16x16x64_i8 v[120:123], v[160:163], v[184:187], v[120:123]
	v_mfma_i32_16x16x64_i8 v[108:111], v[148:151], v[192:195], v[108:111]
	v_mfma_i32_16x16x64_i8 v[104:107], v[160:163], v[192:195], v[104:107]
	v_mfma_i32_16x16x64_i8 v[92:95], v[148:151], v[200:203], v[92:95]
	v_mfma_i32_16x16x64_i8 v[88:91], v[160:163], v[200:203], v[88:91]
	v_mfma_i32_16x16x64_i8 v[76:79], v[148:151], v[208:211], v[76:79]
	v_mfma_i32_16x16x64_i8 v[72:75], v[160:163], v[208:211], v[72:75]
	s_setprio 0
	s_setprio 1
	v_mfma_i32_16x16x64_i8 v[116:119], v[164:167], v[180:183], v[116:119]
	v_mfma_i32_16x16x64_i8 v[112:115], v[172:175], v[180:183], v[112:115]
	v_mfma_i32_16x16x64_i8 v[100:103], v[164:167], v[188:191], v[100:103]
	v_mfma_i32_16x16x64_i8 v[96:99], v[172:175], v[188:191], v[96:99]
	v_mfma_i32_16x16x64_i8 v[84:87], v[164:167], v[196:199], v[84:87]
	v_mfma_i32_16x16x64_i8 v[80:83], v[172:175], v[196:199], v[80:83]
	v_mfma_i32_16x16x64_i8 v[68:71], v[164:167], v[204:207], v[68:71]
	v_mfma_i32_16x16x64_i8 v[64:67], v[172:175], v[204:207], v[64:67]
	v_mfma_i32_16x16x64_i8 v[116:119], v[168:171], v[184:187], v[116:119]
	v_mfma_i32_16x16x64_i8 v[112:115], v[176:179], v[184:187], v[112:115]
	v_mfma_i32_16x16x64_i8 v[100:103], v[168:171], v[192:195], v[100:103]
	v_mfma_i32_16x16x64_i8 v[96:99], v[176:179], v[192:195], v[96:99]
	s_setprio 2
	s_barrier
	v_mfma_i32_16x16x64_i8 v[84:87], v[168:171], v[200:203], v[84:87]
	v_mfma_i32_16x16x64_i8 v[80:83], v[176:179], v[200:203], v[80:83]
	v_mfma_i32_16x16x64_i8 v[68:71], v[168:171], v[208:211], v[68:71]
	v_mfma_i32_16x16x64_i8 v[64:67], v[176:179], v[208:211], v[64:67]
	s_setprio 0
	s_add_i32 s80, s72, s34
	v_lshl_add_u64 v[212:213], s[56:57], 0, v[132:133]
	s_mov_b32 m0, s80
	ds_read_b128 v[180:183], v155 offset:16384
	ds_read_b128 v[184:187], v155 offset:17408
	ds_read_b128 v[188:191], v155 offset:18432
	ds_read_b128 v[192:195], v155 offset:19456
	ds_read_b128 v[196:199], v155 offset:20480
	ds_read_b128 v[200:203], v155 offset:21504
	ds_read_b128 v[204:207], v155 offset:22528
	ds_read_b128 v[208:211], v155 offset:23552
	global_load_lds_dwordx4 v[212:213], off
	s_add_i32 m0, s80, 0x2000
	s_add_u32 s80, s56, 0x80000
	v_lshl_add_u64 v[214:215], s[56:57], 0, v[128:129]
	s_addc_u32 s81, s57, 0
	s_add_i32 s82, s73, s34
	global_load_lds_dwordx4 v[214:215], off
	v_lshl_add_u64 v[216:217], s[80:81], 0, v[132:133]
	s_mov_b32 m0, s82
	v_lshl_add_u64 v[218:219], s[58:59], 0, v[130:131]
	global_load_lds_dwordx4 v[216:217], off
	v_lshl_add_u64 v[216:217], s[80:81], 0, v[128:129]
	s_add_i32 m0, s82, 0x2000
	s_nop 0
	global_load_lds_dwordx4 v[216:217], off
	v_lshl_add_u64 v[216:217], s[58:59], 0, v[134:135]
	s_mov_b32 m0, s37
	s_nop 0
	global_load_lds_dwordx4 v[216:217], off
	s_mov_b32 m0, s45
	s_nop 0
	global_load_lds_dwordx4 v[218:219], off
	s_waitcnt vmcnt(8)
	s_waitcnt lgkmcnt(0)
	s_barrier
	s_setprio 1
	s_waitcnt lgkmcnt(0)
	v_mfma_i32_16x16x64_i8 v[60:63], v[144:147], v[180:183], v[60:63]
	v_mfma_i32_16x16x64_i8 v[56:59], v[156:159], v[180:183], v[56:59]
	v_mfma_i32_16x16x64_i8 v[44:47], v[144:147], v[188:191], v[44:47]
	v_mfma_i32_16x16x64_i8 v[40:43], v[156:159], v[188:191], v[40:43]
	v_mfma_i32_16x16x64_i8 v[28:31], v[144:147], v[196:199], v[28:31]
	v_mfma_i32_16x16x64_i8 v[24:27], v[156:159], v[196:199], v[24:27]
	v_mfma_i32_16x16x64_i8 v[12:15], v[144:147], v[204:207], v[12:15]
	v_mfma_i32_16x16x64_i8 v[8:11], v[156:159], v[204:207], v[8:11]
	v_mfma_i32_16x16x64_i8 v[60:63], v[148:151], v[184:187], v[60:63]
	v_mfma_i32_16x16x64_i8 v[56:59], v[160:163], v[184:187], v[56:59]
	v_mfma_i32_16x16x64_i8 v[44:47], v[148:151], v[192:195], v[44:47]
	v_mfma_i32_16x16x64_i8 v[40:43], v[160:163], v[192:195], v[40:43]
	v_mfma_i32_16x16x64_i8 v[28:31], v[148:151], v[200:203], v[28:31]
	v_mfma_i32_16x16x64_i8 v[24:27], v[160:163], v[200:203], v[24:27]
	v_mfma_i32_16x16x64_i8 v[12:15], v[148:151], v[208:211], v[12:15]
	v_mfma_i32_16x16x64_i8 v[8:11], v[160:163], v[208:211], v[8:11]
	s_setprio 0
	s_setprio 1
	v_mfma_i32_16x16x64_i8 v[52:55], v[164:167], v[180:183], v[52:55]
	v_mfma_i32_16x16x64_i8 v[48:51], v[172:175], v[180:183], v[48:51]
	v_mfma_i32_16x16x64_i8 v[36:39], v[164:167], v[188:191], v[36:39]
	v_mfma_i32_16x16x64_i8 v[32:35], v[172:175], v[188:191], v[32:35]
	v_mfma_i32_16x16x64_i8 v[20:23], v[164:167], v[196:199], v[20:23]
	v_mfma_i32_16x16x64_i8 v[16:19], v[172:175], v[196:199], v[16:19]
	v_mfma_i32_16x16x64_i8 v[4:7], v[164:167], v[204:207], v[4:7]
	v_mfma_i32_16x16x64_i8 v[0:3], v[172:175], v[204:207], v[0:3]
	v_mfma_i32_16x16x64_i8 v[52:55], v[168:171], v[184:187], v[52:55]
	v_mfma_i32_16x16x64_i8 v[48:51], v[176:179], v[184:187], v[48:51]
	v_mfma_i32_16x16x64_i8 v[36:39], v[168:171], v[192:195], v[36:39]
	v_mfma_i32_16x16x64_i8 v[32:35], v[176:179], v[192:195], v[32:35]
	s_setprio 2
	s_barrier
	v_mfma_i32_16x16x64_i8 v[20:23], v[168:171], v[200:203], v[20:23]
	v_mfma_i32_16x16x64_i8 v[16:19], v[176:179], v[200:203], v[16:19]
	v_mfma_i32_16x16x64_i8 v[4:7], v[168:171], v[208:211], v[4:7]
	v_mfma_i32_16x16x64_i8 v[0:3], v[176:179], v[208:211], v[0:3]
	s_setprio 0
	s_add_i32 s80, 0, 0x18000
	s_add_i32 s81, 0, 0x1c000
	v_add_u32_e32 v160, s80, v152
	v_add_u32_e32 v176, s81, v152
	ds_read_b128 v[144:147], v160
	ds_read_b128 v[148:151], v160 offset:1024
	ds_read_b128 v[156:159], v160 offset:2048
	ds_read_b128 v[160:163], v160 offset:3072
	ds_read_b128 v[164:167], v176
	ds_read_b128 v[168:171], v176 offset:1024
	ds_read_b128 v[172:175], v176 offset:2048
	ds_read_b128 v[176:179], v176 offset:3072
	s_add_u32 s58, s58, 0x80000
	s_addc_u32 s59, s59, 0
	s_mov_b32 m0, s53
	v_lshl_add_u64 v[220:221], s[58:59], 0, v[134:135]
	ds_read_b128 v[180:183], v155 offset:32768
	ds_read_b128 v[184:187], v155 offset:33792
	ds_read_b128 v[188:191], v155 offset:34816
	ds_read_b128 v[192:195], v155 offset:35840
	ds_read_b128 v[196:199], v155 offset:36864
	ds_read_b128 v[200:203], v155 offset:37888
	ds_read_b128 v[204:207], v155 offset:38912
	ds_read_b128 v[208:211], v155 offset:39936
	global_load_lds_dwordx4 v[220:221], off
	v_lshl_add_u64 v[220:221], s[58:59], 0, v[130:131]
	s_mov_b32 m0, s60
	s_nop 0
	global_load_lds_dwordx4 v[220:221], off
	s_waitcnt vmcnt(8)
	s_waitcnt lgkmcnt(0)
	s_barrier
	s_setprio 1
	s_waitcnt lgkmcnt(0)
	v_mfma_i32_16x16x64_i8 v[124:127], v[144:147], v[180:183], v[124:127]
	v_mfma_i32_16x16x64_i8 v[120:123], v[156:159], v[180:183], v[120:123]
	v_mfma_i32_16x16x64_i8 v[108:111], v[144:147], v[188:191], v[108:111]
	v_mfma_i32_16x16x64_i8 v[104:107], v[156:159], v[188:191], v[104:107]
	v_mfma_i32_16x16x64_i8 v[92:95], v[144:147], v[196:199], v[92:95]
	v_mfma_i32_16x16x64_i8 v[88:91], v[156:159], v[196:199], v[88:91]
	v_mfma_i32_16x16x64_i8 v[76:79], v[144:147], v[204:207], v[76:79]
	v_mfma_i32_16x16x64_i8 v[72:75], v[156:159], v[204:207], v[72:75]
	v_mfma_i32_16x16x64_i8 v[124:127], v[148:151], v[184:187], v[124:127]
	v_mfma_i32_16x16x64_i8 v[120:123], v[160:163], v[184:187], v[120:123]
	v_mfma_i32_16x16x64_i8 v[108:111], v[148:151], v[192:195], v[108:111]
	v_mfma_i32_16x16x64_i8 v[104:107], v[160:163], v[192:195], v[104:107]
	v_mfma_i32_16x16x64_i8 v[92:95], v[148:151], v[200:203], v[92:95]
	v_mfma_i32_16x16x64_i8 v[88:91], v[160:163], v[200:203], v[88:91]
	v_mfma_i32_16x16x64_i8 v[76:79], v[148:151], v[208:211], v[76:79]
	v_mfma_i32_16x16x64_i8 v[72:75], v[160:163], v[208:211], v[72:75]
	s_setprio 0
	s_setprio 1
	v_mfma_i32_16x16x64_i8 v[116:119], v[164:167], v[180:183], v[116:119]
	v_mfma_i32_16x16x64_i8 v[112:115], v[172:175], v[180:183], v[112:115]
	v_mfma_i32_16x16x64_i8 v[100:103], v[164:167], v[188:191], v[100:103]
	v_mfma_i32_16x16x64_i8 v[96:99], v[172:175], v[188:191], v[96:99]
	v_mfma_i32_16x16x64_i8 v[84:87], v[164:167], v[196:199], v[84:87]
	v_mfma_i32_16x16x64_i8 v[80:83], v[172:175], v[196:199], v[80:83]
	v_mfma_i32_16x16x64_i8 v[68:71], v[164:167], v[204:207], v[68:71]
	v_mfma_i32_16x16x64_i8 v[64:67], v[172:175], v[204:207], v[64:67]
	v_mfma_i32_16x16x64_i8 v[116:119], v[168:171], v[184:187], v[116:119]
	v_mfma_i32_16x16x64_i8 v[112:115], v[176:179], v[184:187], v[112:115]
	v_mfma_i32_16x16x64_i8 v[100:103], v[168:171], v[192:195], v[100:103]
	v_mfma_i32_16x16x64_i8 v[96:99], v[176:179], v[192:195], v[96:99]
	s_setprio 2
	s_barrier
	v_mfma_i32_16x16x64_i8 v[84:87], v[168:171], v[200:203], v[84:87]
	v_mfma_i32_16x16x64_i8 v[80:83], v[176:179], v[200:203], v[80:83]
	v_mfma_i32_16x16x64_i8 v[68:71], v[168:171], v[208:211], v[68:71]
	v_mfma_i32_16x16x64_i8 v[64:67], v[176:179], v[208:211], v[64:67]
	s_setprio 0
	s_add_i32 s58, s80, s34
	v_lshl_add_u64 v[212:213], v[212:213], 0, s[26:27]
	s_mov_b32 m0, s58
	ds_read_b128 v[180:183], v155 offset:49152
	ds_read_b128 v[184:187], v155 offset:50176
	ds_read_b128 v[188:191], v155 offset:51200
	ds_read_b128 v[192:195], v155 offset:52224
	ds_read_b128 v[196:199], v155 offset:53248
	ds_read_b128 v[200:203], v155 offset:54272
	ds_read_b128 v[204:207], v155 offset:55296
	ds_read_b128 v[208:211], v155 offset:56320
	global_load_lds_dwordx4 v[212:213], off
	s_add_i32 m0, s58, 0x2000
	s_add_u32 s56, s56, 0x80080
	v_lshl_add_u64 v[212:213], v[214:215], 0, s[26:27]
	s_addc_u32 s57, s57, 0
	s_add_i32 s58, s81, s34
	global_load_lds_dwordx4 v[212:213], off
	v_lshl_add_u64 v[212:213], s[56:57], 0, v[132:133]
	s_mov_b32 m0, s58
	s_nop 0
	global_load_lds_dwordx4 v[212:213], off
	v_lshl_add_u64 v[212:213], s[56:57], 0, v[128:129]
	s_add_i32 m0, s58, 0x2000
	s_nop 0
	global_load_lds_dwordx4 v[212:213], off
	v_lshl_add_u64 v[212:213], v[216:217], 0, s[26:27]
	s_mov_b32 m0, s63
	s_nop 0
	global_load_lds_dwordx4 v[212:213], off
	v_lshl_add_u64 v[212:213], v[218:219], 0, s[26:27]
	s_mov_b32 m0, s70
	s_nop 0
	global_load_lds_dwordx4 v[212:213], off
	s_waitcnt vmcnt(8)
	s_waitcnt lgkmcnt(0)
	s_barrier
	s_setprio 1
	s_waitcnt lgkmcnt(0)
	v_mfma_i32_16x16x64_i8 v[60:63], v[144:147], v[180:183], v[60:63]
	v_mfma_i32_16x16x64_i8 v[56:59], v[156:159], v[180:183], v[56:59]
	v_mfma_i32_16x16x64_i8 v[44:47], v[144:147], v[188:191], v[44:47]
	v_mfma_i32_16x16x64_i8 v[40:43], v[156:159], v[188:191], v[40:43]
	v_mfma_i32_16x16x64_i8 v[28:31], v[144:147], v[196:199], v[28:31]
	v_mfma_i32_16x16x64_i8 v[24:27], v[156:159], v[196:199], v[24:27]
	v_mfma_i32_16x16x64_i8 v[12:15], v[144:147], v[204:207], v[12:15]
	v_mfma_i32_16x16x64_i8 v[8:11], v[156:159], v[204:207], v[8:11]
	v_mfma_i32_16x16x64_i8 v[60:63], v[148:151], v[184:187], v[60:63]
	v_mfma_i32_16x16x64_i8 v[56:59], v[160:163], v[184:187], v[56:59]
	v_mfma_i32_16x16x64_i8 v[44:47], v[148:151], v[192:195], v[44:47]
	v_mfma_i32_16x16x64_i8 v[40:43], v[160:163], v[192:195], v[40:43]
	v_mfma_i32_16x16x64_i8 v[28:31], v[148:151], v[200:203], v[28:31]
	v_mfma_i32_16x16x64_i8 v[24:27], v[160:163], v[200:203], v[24:27]
	v_mfma_i32_16x16x64_i8 v[12:15], v[148:151], v[208:211], v[12:15]
	v_mfma_i32_16x16x64_i8 v[8:11], v[160:163], v[208:211], v[8:11]
	s_setprio 0
	s_setprio 1
	v_mfma_i32_16x16x64_i8 v[52:55], v[164:167], v[180:183], v[52:55]
	v_mfma_i32_16x16x64_i8 v[48:51], v[172:175], v[180:183], v[48:51]
	v_mfma_i32_16x16x64_i8 v[36:39], v[164:167], v[188:191], v[36:39]
	v_mfma_i32_16x16x64_i8 v[32:35], v[172:175], v[188:191], v[32:35]
	v_mfma_i32_16x16x64_i8 v[20:23], v[164:167], v[196:199], v[20:23]
	v_mfma_i32_16x16x64_i8 v[16:19], v[172:175], v[196:199], v[16:19]
	v_mfma_i32_16x16x64_i8 v[4:7], v[164:167], v[204:207], v[4:7]
	v_mfma_i32_16x16x64_i8 v[0:3], v[172:175], v[204:207], v[0:3]
	v_mfma_i32_16x16x64_i8 v[52:55], v[168:171], v[184:187], v[52:55]
	v_mfma_i32_16x16x64_i8 v[48:51], v[176:179], v[184:187], v[48:51]
	v_mfma_i32_16x16x64_i8 v[36:39], v[168:171], v[192:195], v[36:39]
	v_mfma_i32_16x16x64_i8 v[32:35], v[176:179], v[192:195], v[32:35]
	s_setprio 2
	s_barrier
	v_mfma_i32_16x16x64_i8 v[20:23], v[168:171], v[200:203], v[20:23]
	v_mfma_i32_16x16x64_i8 v[16:19], v[176:179], v[200:203], v[16:19]
	v_mfma_i32_16x16x64_i8 v[4:7], v[168:171], v[208:211], v[4:7]
	v_mfma_i32_16x16x64_i8 v[0:3], v[176:179], v[208:211], v[0:3]
	s_setprio 0
	s_add_i32 s79, s79, 2
	s_add_u32 s54, s54, 0x100
	s_addc_u32 s55, s55, 0
	s_add_u32 s77, s77, 0x100
	s_addc_u32 s78, s78, 0
	s_cmp_gt_u32 s79, 29
	s_cbranch_scc0 .LBB0_771

.LBB0_978:
	ds_read_b128 v[144:147], v153
	ds_read_b128 v[148:151], v153 offset:1024
	ds_read_b128 v[156:159], v153 offset:2048
	ds_read_b128 v[160:163], v153 offset:3072
	ds_read_b128 v[164:167], v154
	ds_read_b128 v[168:171], v154 offset:1024
	ds_read_b128 v[172:175], v154 offset:2048
	ds_read_b128 v[176:179], v154 offset:3072
	s_add_u32 s46, s40, 0x100
	s_addc_u32 s47, s41, 0
	s_cmpk_eq_i32 s77, 0x52
	s_cselect_b32 s51, s9, s47
	s_cselect_b32 s50, s8, s46
	s_cselect_b32 s49, s39, s76
	s_cselect_b32 s48, s38, s75
	v_lshl_add_u64 v[212:213], s[40:41], 0, v[136:137]
	s_add_i32 m0, s52, 0xc000
	ds_read_b128 v[180:183], v155
	ds_read_b128 v[184:187], v155 offset:1024
	ds_read_b128 v[188:191], v155 offset:2048
	ds_read_b128 v[192:195], v155 offset:3072
	ds_read_b128 v[196:199], v155 offset:4096
	ds_read_b128 v[200:203], v155 offset:5120
	ds_read_b128 v[204:207], v155 offset:6144
	ds_read_b128 v[208:211], v155 offset:7168
	global_load_lds_dwordx4 v[212:213], off
	v_lshl_add_u64 v[212:213], s[40:41], 0, v[138:139]
	s_add_i32 m0, s52, 0xe000
	s_nop 0
	global_load_lds_dwordx4 v[212:213], off
	s_waitcnt vmcnt(8)
	s_waitcnt lgkmcnt(0)
	s_barrier
	s_setprio 1
	s_waitcnt lgkmcnt(0)
	v_mfma_i32_16x16x64_i8 v[124:127], v[144:147], v[180:183], v[124:127]
	v_mfma_i32_16x16x64_i8 v[120:123], v[156:159], v[180:183], v[120:123]
	v_mfma_i32_16x16x64_i8 v[108:111], v[144:147], v[188:191], v[108:111]
	v_mfma_i32_16x16x64_i8 v[104:107], v[156:159], v[188:191], v[104:107]
	v_mfma_i32_16x16x64_i8 v[92:95], v[144:147], v[196:199], v[92:95]
	v_mfma_i32_16x16x64_i8 v[88:91], v[156:159], v[196:199], v[88:91]
	v_mfma_i32_16x16x64_i8 v[76:79], v[144:147], v[204:207], v[76:79]
	v_mfma_i32_16x16x64_i8 v[72:75], v[156:159], v[204:207], v[72:75]
	v_mfma_i32_16x16x64_i8 v[124:127], v[148:151], v[184:187], v[124:127]
	v_mfma_i32_16x16x64_i8 v[120:123], v[160:163], v[184:187], v[120:123]
	v_mfma_i32_16x16x64_i8 v[108:111], v[148:151], v[192:195], v[108:111]
	v_mfma_i32_16x16x64_i8 v[104:107], v[160:163], v[192:195], v[104:107]
	v_mfma_i32_16x16x64_i8 v[92:95], v[148:151], v[200:203], v[92:95]
	v_mfma_i32_16x16x64_i8 v[88:91], v[160:163], v[200:203], v[88:91]
	v_mfma_i32_16x16x64_i8 v[76:79], v[148:151], v[208:211], v[76:79]
	v_mfma_i32_16x16x64_i8 v[72:75], v[160:163], v[208:211], v[72:75]
	s_setprio 0
	s_setprio 1
	v_mfma_i32_16x16x64_i8 v[116:119], v[164:167], v[180:183], v[116:119]
	v_mfma_i32_16x16x64_i8 v[112:115], v[172:175], v[180:183], v[112:115]
	v_mfma_i32_16x16x64_i8 v[100:103], v[164:167], v[188:191], v[100:103]
	v_mfma_i32_16x16x64_i8 v[96:99], v[172:175], v[188:191], v[96:99]
	v_mfma_i32_16x16x64_i8 v[84:87], v[164:167], v[196:199], v[84:87]
	v_mfma_i32_16x16x64_i8 v[80:83], v[172:175], v[196:199], v[80:83]
	v_mfma_i32_16x16x64_i8 v[68:71], v[164:167], v[204:207], v[68:71]
	v_mfma_i32_16x16x64_i8 v[64:67], v[172:175], v[204:207], v[64:67]
	v_mfma_i32_16x16x64_i8 v[116:119], v[168:171], v[184:187], v[116:119]
	v_mfma_i32_16x16x64_i8 v[112:115], v[176:179], v[184:187], v[112:115]
	v_mfma_i32_16x16x64_i8 v[100:103], v[168:171], v[192:195], v[100:103]
	v_mfma_i32_16x16x64_i8 v[96:99], v[176:179], v[192:195], v[96:99]
	s_setprio 2
	s_barrier
	v_mfma_i32_16x16x64_i8 v[84:87], v[168:171], v[200:203], v[84:87]
	v_mfma_i32_16x16x64_i8 v[80:83], v[176:179], v[200:203], v[80:83]
	v_mfma_i32_16x16x64_i8 v[68:71], v[168:171], v[208:211], v[68:71]
	v_mfma_i32_16x16x64_i8 v[64:67], v[176:179], v[208:211], v[64:67]
	s_setprio 0
	s_add_i32 s40, s61, s35
	v_lshl_add_u64 v[212:213], s[48:49], 0, v[132:133]
	s_mov_b32 m0, s40
	ds_read_b128 v[180:183], v155 offset:16384
	ds_read_b128 v[184:187], v155 offset:17408
	ds_read_b128 v[188:191], v155 offset:18432
	ds_read_b128 v[192:195], v155 offset:19456
	ds_read_b128 v[196:199], v155 offset:20480
	ds_read_b128 v[200:203], v155 offset:21504
	ds_read_b128 v[204:207], v155 offset:22528
	ds_read_b128 v[208:211], v155 offset:23552
	global_load_lds_dwordx4 v[212:213], off
	s_add_i32 m0, s40, 0x2000
	s_add_u32 s40, s48, 0x158000
	v_lshl_add_u64 v[214:215], s[48:49], 0, v[128:129]
	s_addc_u32 s41, s49, 0
	s_add_i32 s78, s62, s35
	global_load_lds_dwordx4 v[214:215], off
	v_lshl_add_u64 v[216:217], s[40:41], 0, v[132:133]
	s_mov_b32 m0, s78
	v_lshl_add_u64 v[218:219], s[50:51], 0, v[130:131]
	global_load_lds_dwordx4 v[216:217], off
	v_lshl_add_u64 v[216:217], s[40:41], 0, v[128:129]
	s_add_i32 m0, s78, 0x2000
	s_nop 0
	global_load_lds_dwordx4 v[216:217], off
	v_lshl_add_u64 v[216:217], s[50:51], 0, v[134:135]
	s_mov_b32 m0, s52
	s_nop 0
	global_load_lds_dwordx4 v[216:217], off
	s_mov_b32 m0, s53
	s_nop 0
	global_load_lds_dwordx4 v[218:219], off
	s_waitcnt vmcnt(8)
	s_waitcnt lgkmcnt(0)
	s_barrier
	s_setprio 1
	s_waitcnt lgkmcnt(0)
	v_mfma_i32_16x16x64_i8 v[60:63], v[144:147], v[180:183], v[60:63]
	v_mfma_i32_16x16x64_i8 v[56:59], v[156:159], v[180:183], v[56:59]
	v_mfma_i32_16x16x64_i8 v[44:47], v[144:147], v[188:191], v[44:47]
	v_mfma_i32_16x16x64_i8 v[40:43], v[156:159], v[188:191], v[40:43]
	v_mfma_i32_16x16x64_i8 v[28:31], v[144:147], v[196:199], v[28:31]
	v_mfma_i32_16x16x64_i8 v[24:27], v[156:159], v[196:199], v[24:27]
	v_mfma_i32_16x16x64_i8 v[12:15], v[144:147], v[204:207], v[12:15]
	v_mfma_i32_16x16x64_i8 v[8:11], v[156:159], v[204:207], v[8:11]
	v_mfma_i32_16x16x64_i8 v[60:63], v[148:151], v[184:187], v[60:63]
	v_mfma_i32_16x16x64_i8 v[56:59], v[160:163], v[184:187], v[56:59]
	v_mfma_i32_16x16x64_i8 v[44:47], v[148:151], v[192:195], v[44:47]
	v_mfma_i32_16x16x64_i8 v[40:43], v[160:163], v[192:195], v[40:43]
	v_mfma_i32_16x16x64_i8 v[28:31], v[148:151], v[200:203], v[28:31]
	v_mfma_i32_16x16x64_i8 v[24:27], v[160:163], v[200:203], v[24:27]
	v_mfma_i32_16x16x64_i8 v[12:15], v[148:151], v[208:211], v[12:15]
	v_mfma_i32_16x16x64_i8 v[8:11], v[160:163], v[208:211], v[8:11]
	s_setprio 0
	s_setprio 1
	v_mfma_i32_16x16x64_i8 v[52:55], v[164:167], v[180:183], v[52:55]
	v_mfma_i32_16x16x64_i8 v[48:51], v[172:175], v[180:183], v[48:51]
	v_mfma_i32_16x16x64_i8 v[36:39], v[164:167], v[188:191], v[36:39]
	v_mfma_i32_16x16x64_i8 v[32:35], v[172:175], v[188:191], v[32:35]
	v_mfma_i32_16x16x64_i8 v[20:23], v[164:167], v[196:199], v[20:23]
	v_mfma_i32_16x16x64_i8 v[16:19], v[172:175], v[196:199], v[16:19]
	v_mfma_i32_16x16x64_i8 v[4:7], v[164:167], v[204:207], v[4:7]
	v_mfma_i32_16x16x64_i8 v[0:3], v[172:175], v[204:207], v[0:3]
	v_mfma_i32_16x16x64_i8 v[52:55], v[168:171], v[184:187], v[52:55]
	v_mfma_i32_16x16x64_i8 v[48:51], v[176:179], v[184:187], v[48:51]
	v_mfma_i32_16x16x64_i8 v[36:39], v[168:171], v[192:195], v[36:39]
	v_mfma_i32_16x16x64_i8 v[32:35], v[176:179], v[192:195], v[32:35]
	s_setprio 2
	s_barrier
	v_mfma_i32_16x16x64_i8 v[20:23], v[168:171], v[200:203], v[20:23]
	v_mfma_i32_16x16x64_i8 v[16:19], v[176:179], v[200:203], v[16:19]
	v_mfma_i32_16x16x64_i8 v[4:7], v[168:171], v[208:211], v[4:7]
	v_mfma_i32_16x16x64_i8 v[0:3], v[176:179], v[208:211], v[0:3]
	s_setprio 0
	s_add_i32 s78, 0, 0x18000
	s_add_i32 s79, 0, 0x1c000
	v_add_u32_e32 v160, s78, v152
	v_add_u32_e32 v176, s79, v152
	ds_read_b128 v[144:147], v160
	ds_read_b128 v[148:151], v160 offset:1024
	ds_read_b128 v[156:159], v160 offset:2048
	ds_read_b128 v[160:163], v160 offset:3072
	ds_read_b128 v[164:167], v176
	ds_read_b128 v[168:171], v176 offset:1024
	ds_read_b128 v[172:175], v176 offset:2048
	ds_read_b128 v[176:179], v176 offset:3072
	s_add_u32 s40, s50, 0x158000
	s_addc_u32 s41, s51, 0
	s_mov_b32 m0, s54
	v_lshl_add_u64 v[220:221], s[40:41], 0, v[134:135]
	ds_read_b128 v[180:183], v155 offset:32768
	ds_read_b128 v[184:187], v155 offset:33792
	ds_read_b128 v[188:191], v155 offset:34816
	ds_read_b128 v[192:195], v155 offset:35840
	ds_read_b128 v[196:199], v155 offset:36864
	ds_read_b128 v[200:203], v155 offset:37888
	ds_read_b128 v[204:207], v155 offset:38912
	ds_read_b128 v[208:211], v155 offset:39936
	global_load_lds_dwordx4 v[220:221], off
	v_lshl_add_u64 v[220:221], s[40:41], 0, v[130:131]
	s_mov_b32 m0, s55
	s_nop 0
	global_load_lds_dwordx4 v[220:221], off
	s_waitcnt vmcnt(8)
	s_waitcnt lgkmcnt(0)
	s_barrier
	s_setprio 1
	s_waitcnt lgkmcnt(0)
	v_mfma_i32_16x16x64_i8 v[124:127], v[144:147], v[180:183], v[124:127]
	v_mfma_i32_16x16x64_i8 v[120:123], v[156:159], v[180:183], v[120:123]
	v_mfma_i32_16x16x64_i8 v[108:111], v[144:147], v[188:191], v[108:111]
	v_mfma_i32_16x16x64_i8 v[104:107], v[156:159], v[188:191], v[104:107]
	v_mfma_i32_16x16x64_i8 v[92:95], v[144:147], v[196:199], v[92:95]
	v_mfma_i32_16x16x64_i8 v[88:91], v[156:159], v[196:199], v[88:91]
	v_mfma_i32_16x16x64_i8 v[76:79], v[144:147], v[204:207], v[76:79]
	v_mfma_i32_16x16x64_i8 v[72:75], v[156:159], v[204:207], v[72:75]
	v_mfma_i32_16x16x64_i8 v[124:127], v[148:151], v[184:187], v[124:127]
	v_mfma_i32_16x16x64_i8 v[120:123], v[160:163], v[184:187], v[120:123]
	v_mfma_i32_16x16x64_i8 v[108:111], v[148:151], v[192:195], v[108:111]
	v_mfma_i32_16x16x64_i8 v[104:107], v[160:163], v[192:195], v[104:107]
	v_mfma_i32_16x16x64_i8 v[92:95], v[148:151], v[200:203], v[92:95]
	v_mfma_i32_16x16x64_i8 v[88:91], v[160:163], v[200:203], v[88:91]
	v_mfma_i32_16x16x64_i8 v[76:79], v[148:151], v[208:211], v[76:79]
	v_mfma_i32_16x16x64_i8 v[72:75], v[160:163], v[208:211], v[72:75]
	s_setprio 0
	s_setprio 1
	v_mfma_i32_16x16x64_i8 v[116:119], v[164:167], v[180:183], v[116:119]
	v_mfma_i32_16x16x64_i8 v[112:115], v[172:175], v[180:183], v[112:115]
	v_mfma_i32_16x16x64_i8 v[100:103], v[164:167], v[188:191], v[100:103]
	v_mfma_i32_16x16x64_i8 v[96:99], v[172:175], v[188:191], v[96:99]
	v_mfma_i32_16x16x64_i8 v[84:87], v[164:167], v[196:199], v[84:87]
	v_mfma_i32_16x16x64_i8 v[80:83], v[172:175], v[196:199], v[80:83]
	v_mfma_i32_16x16x64_i8 v[68:71], v[164:167], v[204:207], v[68:71]
	v_mfma_i32_16x16x64_i8 v[64:67], v[172:175], v[204:207], v[64:67]
	v_mfma_i32_16x16x64_i8 v[116:119], v[168:171], v[184:187], v[116:119]
	v_mfma_i32_16x16x64_i8 v[112:115], v[176:179], v[184:187], v[112:115]
	v_mfma_i32_16x16x64_i8 v[100:103], v[168:171], v[192:195], v[100:103]
	v_mfma_i32_16x16x64_i8 v[96:99], v[176:179], v[192:195], v[96:99]
	s_setprio 2
	s_barrier
	v_mfma_i32_16x16x64_i8 v[84:87], v[168:171], v[200:203], v[84:87]
	v_mfma_i32_16x16x64_i8 v[80:83], v[176:179], v[200:203], v[80:83]
	v_mfma_i32_16x16x64_i8 v[68:71], v[168:171], v[208:211], v[68:71]
	v_mfma_i32_16x16x64_i8 v[64:67], v[176:179], v[208:211], v[64:67]
	s_setprio 0
	s_add_i32 s40, s78, s35
	v_lshl_add_u64 v[212:213], v[212:213], 0, s[20:21]
	s_mov_b32 m0, s40
	ds_read_b128 v[180:183], v155 offset:49152
	ds_read_b128 v[184:187], v155 offset:50176
	ds_read_b128 v[188:191], v155 offset:51200
	ds_read_b128 v[192:195], v155 offset:52224
	ds_read_b128 v[196:199], v155 offset:53248
	ds_read_b128 v[200:203], v155 offset:54272
	ds_read_b128 v[204:207], v155 offset:55296
	ds_read_b128 v[208:211], v155 offset:56320
	global_load_lds_dwordx4 v[212:213], off
	s_add_i32 m0, s40, 0x2000
	s_add_u32 s40, s48, 0x158080
	v_lshl_add_u64 v[212:213], v[214:215], 0, s[20:21]
	s_addc_u32 s41, s49, 0
	s_add_i32 s48, s79, s35
	global_load_lds_dwordx4 v[212:213], off
	v_lshl_add_u64 v[212:213], s[40:41], 0, v[132:133]
	s_mov_b32 m0, s48
	s_nop 0
	global_load_lds_dwordx4 v[212:213], off
	v_lshl_add_u64 v[212:213], s[40:41], 0, v[128:129]
	s_add_i32 m0, s48, 0x2000
	s_nop 0
	global_load_lds_dwordx4 v[212:213], off
	v_lshl_add_u64 v[212:213], v[216:217], 0, s[20:21]
	s_mov_b32 m0, s58
	s_nop 0
	global_load_lds_dwordx4 v[212:213], off
	v_lshl_add_u64 v[212:213], v[218:219], 0, s[20:21]
	s_mov_b32 m0, s59
	s_nop 0
	global_load_lds_dwordx4 v[212:213], off
	s_waitcnt vmcnt(8)
	s_waitcnt lgkmcnt(0)
	s_barrier
	s_setprio 1
	s_waitcnt lgkmcnt(0)
	v_mfma_i32_16x16x64_i8 v[60:63], v[144:147], v[180:183], v[60:63]
	v_mfma_i32_16x16x64_i8 v[56:59], v[156:159], v[180:183], v[56:59]
	v_mfma_i32_16x16x64_i8 v[44:47], v[144:147], v[188:191], v[44:47]
	v_mfma_i32_16x16x64_i8 v[40:43], v[156:159], v[188:191], v[40:43]
	v_mfma_i32_16x16x64_i8 v[28:31], v[144:147], v[196:199], v[28:31]
	v_mfma_i32_16x16x64_i8 v[24:27], v[156:159], v[196:199], v[24:27]
	v_mfma_i32_16x16x64_i8 v[12:15], v[144:147], v[204:207], v[12:15]
	v_mfma_i32_16x16x64_i8 v[8:11], v[156:159], v[204:207], v[8:11]
	v_mfma_i32_16x16x64_i8 v[60:63], v[148:151], v[184:187], v[60:63]
	v_mfma_i32_16x16x64_i8 v[56:59], v[160:163], v[184:187], v[56:59]
	v_mfma_i32_16x16x64_i8 v[44:47], v[148:151], v[192:195], v[44:47]
	v_mfma_i32_16x16x64_i8 v[40:43], v[160:163], v[192:195], v[40:43]
	v_mfma_i32_16x16x64_i8 v[28:31], v[148:151], v[200:203], v[28:31]
	v_mfma_i32_16x16x64_i8 v[24:27], v[160:163], v[200:203], v[24:27]
	v_mfma_i32_16x16x64_i8 v[12:15], v[148:151], v[208:211], v[12:15]
	v_mfma_i32_16x16x64_i8 v[8:11], v[160:163], v[208:211], v[8:11]
	s_setprio 0
	s_setprio 1
	v_mfma_i32_16x16x64_i8 v[52:55], v[164:167], v[180:183], v[52:55]
	v_mfma_i32_16x16x64_i8 v[48:51], v[172:175], v[180:183], v[48:51]
	v_mfma_i32_16x16x64_i8 v[36:39], v[164:167], v[188:191], v[36:39]
	v_mfma_i32_16x16x64_i8 v[32:35], v[172:175], v[188:191], v[32:35]
	v_mfma_i32_16x16x64_i8 v[20:23], v[164:167], v[196:199], v[20:23]
	v_mfma_i32_16x16x64_i8 v[16:19], v[172:175], v[196:199], v[16:19]
	v_mfma_i32_16x16x64_i8 v[4:7], v[164:167], v[204:207], v[4:7]
	v_mfma_i32_16x16x64_i8 v[0:3], v[172:175], v[204:207], v[0:3]
	v_mfma_i32_16x16x64_i8 v[52:55], v[168:171], v[184:187], v[52:55]
	v_mfma_i32_16x16x64_i8 v[48:51], v[176:179], v[184:187], v[48:51]
	v_mfma_i32_16x16x64_i8 v[36:39], v[168:171], v[192:195], v[36:39]
	v_mfma_i32_16x16x64_i8 v[32:35], v[176:179], v[192:195], v[32:35]
	s_setprio 2
	s_barrier
	v_mfma_i32_16x16x64_i8 v[20:23], v[168:171], v[200:203], v[20:23]
	v_mfma_i32_16x16x64_i8 v[16:19], v[176:179], v[200:203], v[16:19]
	v_mfma_i32_16x16x64_i8 v[4:7], v[168:171], v[208:211], v[4:7]
	v_mfma_i32_16x16x64_i8 v[0:3], v[176:179], v[208:211], v[0:3]
	s_setprio 0
	s_add_i32 s77, s77, 2
	s_add_u32 s75, s75, 0x100
	s_addc_u32 s76, s76, 0
	s_cmpk_gt_u32 s77, 0x53
	s_mov_b64 s[40:41], s[46:47]
	s_cbranch_scc0 .LBB0_978
